# K=4096 loops: both prefetch load groups issued before their barriers
# baseline (speedup 1.0000x reference)
.LBB0_358:
	v_lshl_add_u64 v[142:143], v[142:143], 0, s[14:15]
	v_lshl_add_u64 v[144:145], v[144:145], 0, s[14:15]
	s_and_b64 vcc, exec, s[18:19]
	s_cbranch_vccnz .Lk5_exit
	s_add_i32 s12, s12, 2
	s_cmp_lt_u32 s12, 62
	s_cselect_b64 s[20:21], -1, 0
	s_cmp_gt_u32 s12, 61
	s_cselect_b64 s[18:19], -1, 0
	s_and_b64 vcc, exec, s[18:19]
	v_lshl_add_u64 v[148:149], v[144:145], 0, v[138:139]
	v_lshl_add_u64 v[146:147], v[142:143], 0, v[138:139]
	s_cbranch_vccnz .Lk5_noP0
	v_add_co_u32_e32 v66, vcc, 0xb6c0000, v148
	s_nop 1
	v_addc_co_u32_e32 v67, vcc, 0, v149, vcc
	v_add_co_u32_e32 v70, vcc, 0xb700000, v148
	s_nop 1
	v_addc_co_u32_e32 v71, vcc, 0, v149, vcc
	v_add_co_u32_e32 v74, vcc, 0xb740000, v148
	global_load_dwordx4 v[66:69], v[66:67], off offset:512
	s_nop 0
	global_load_dwordx4 v[70:73], v[70:71], off offset:512
	v_addc_co_u32_e32 v75, vcc, 0, v149, vcc
	v_add_co_u32_e32 v78, vcc, 0xb780000, v148
	s_nop 1
	v_addc_co_u32_e32 v79, vcc, 0, v149, vcc
	v_add_co_u32_e32 v82, vcc, 0x10c0000, v146
	global_load_dwordx4 v[74:77], v[74:75], off offset:512
	s_nop 0
	global_load_dwordx4 v[78:81], v[78:79], off offset:512
	v_addc_co_u32_e32 v83, vcc, 0, v147, vcc
	v_add_co_u32_e32 v86, vcc, 0x1100000, v146
	s_nop 1
	v_addc_co_u32_e32 v87, vcc, 0, v147, vcc
	v_add_co_u32_e32 v98, vcc, 0x1140000, v146
	global_load_dwordx4 v[82:85], v[82:83], off offset:256
	s_nop 0
	global_load_dwordx4 v[86:89], v[86:87], off offset:256
	v_addc_co_u32_e32 v99, vcc, 0, v147, vcc
	v_add_co_u32_e32 v110, vcc, 0x1180000, v146
	s_nop 1
	v_addc_co_u32_e32 v111, vcc, 0, v147, vcc
	global_load_dwordx4 v[98:101], v[98:99], off offset:256
	s_nop 0
	global_load_dwordx4 v[110:113], v[110:111], off offset:256
.Lk5_noP0:
	s_waitcnt lgkmcnt(0)
	s_barrier
	s_branch .LBB0_361

.Lk5_join:
	s_cbranch_scc1 .Lk5_noP1
	v_add_co_u32_e32 v90, vcc, 0xb6c0000, v148
	s_nop 1
	v_addc_co_u32_e32 v91, vcc, 0, v149, vcc
	v_add_co_u32_e32 v94, vcc, 0xb700000, v148
	s_nop 1
	v_addc_co_u32_e32 v95, vcc, 0, v149, vcc
	v_add_co_u32_e32 v102, vcc, 0xb740000, v148
	global_load_dwordx4 v[90:93], v[90:91], off offset:640
	s_nop 0
	global_load_dwordx4 v[94:97], v[94:95], off offset:640
	v_addc_co_u32_e32 v103, vcc, 0, v149, vcc
	v_add_co_u32_e32 v106, vcc, 0xb780000, v148
	s_nop 1
	v_addc_co_u32_e32 v107, vcc, 0, v149, vcc
	v_add_co_u32_e32 v114, vcc, 0x10c0000, v146
	global_load_dwordx4 v[102:105], v[102:103], off offset:640
	s_nop 0
	global_load_dwordx4 v[106:109], v[106:107], off offset:640
	v_addc_co_u32_e32 v115, vcc, 0, v147, vcc
	v_add_co_u32_e32 v118, vcc, 0x1100000, v146
	s_nop 1
	v_addc_co_u32_e32 v119, vcc, 0, v147, vcc
	v_add_co_u32_e32 v122, vcc, 0x1140000, v146
	global_load_dwordx4 v[114:117], v[114:115], off offset:384
	s_nop 0
	global_load_dwordx4 v[118:121], v[118:119], off offset:384
	v_addc_co_u32_e32 v123, vcc, 0, v147, vcc
	v_add_co_u32_e32 v126, vcc, 0x1180000, v146
	s_nop 1
	v_addc_co_u32_e32 v127, vcc, 0, v147, vcc
	global_load_dwordx4 v[122:125], v[122:123], off offset:384
	s_nop 0
	global_load_dwordx4 v[126:129], v[126:127], off offset:384
.Lk5_noP1:
	s_waitcnt lgkmcnt(0)
	s_barrier
	v_mfma_f32_32x32x16_bf16 v[18:33], v[162:165], v[166:169], v[18:33]
	v_mfma_f32_32x32x16_bf16 v[2:17], v[162:165], v[178:181], v[2:17]
	v_mfma_f32_32x32x16_bf16 v[50:65], v[170:173], v[174:177], v[50:65]
	v_mfma_f32_32x32x16_bf16 v[34:49], v[170:173], v[182:185], v[34:49]
	v_mfma_f32_32x32x16_bf16 v[18:33], v[186:189], v[174:177], v[18:33]
	v_mfma_f32_32x32x16_bf16 v[2:17], v[186:189], v[182:185], v[2:17]
.LBB0_363:
	ds_read_b128 v[146:149], v130 offset:18432
	ds_read_b128 v[162:165], v131 offset:55296
	ds_read_b128 v[166:169], v130 offset:18464
	ds_read_b128 v[170:173], v131 offset:55328
	ds_read_b128 v[174:177], v131 offset:59904
	ds_read_b128 v[178:181], v131 offset:59936
	s_andn2_b64 vcc, exec, s[20:21]
	s_waitcnt lgkmcnt(4)
	v_mfma_f32_32x32x16_bf16 v[50:65], v[146:149], v[162:165], v[50:65]
	s_waitcnt lgkmcnt(1)
	v_mfma_f32_32x32x16_bf16 v[34:49], v[146:149], v[174:177], v[34:49]
	ds_read_b128 v[146:149], v130 offset:23040
	ds_read_b128 v[182:185], v130 offset:23072
	s_waitcnt lgkmcnt(1)
	v_mfma_f32_32x32x16_bf16 v[18:33], v[146:149], v[162:165], v[18:33]
	v_mfma_f32_32x32x16_bf16 v[2:17], v[146:149], v[174:177], v[2:17]
	v_mfma_f32_32x32x16_bf16 v[50:65], v[166:169], v[170:173], v[50:65]
	v_mfma_f32_32x32x16_bf16 v[34:49], v[166:169], v[178:181], v[34:49]
	s_waitcnt lgkmcnt(0)
	v_mfma_f32_32x32x16_bf16 v[18:33], v[182:185], v[170:173], v[18:33]
	ds_read_b128 v[146:149], v130 offset:18496
	ds_read_b128 v[162:165], v131 offset:55360
	ds_read_b128 v[166:169], v130 offset:18528
	ds_read_b128 v[170:173], v131 offset:55392
	v_mfma_f32_32x32x16_bf16 v[2:17], v[182:185], v[178:181], v[2:17]
	ds_read_b128 v[174:177], v131 offset:59968
	ds_read_b128 v[178:181], v131 offset:60000
	s_waitcnt lgkmcnt(4)
	v_mfma_f32_32x32x16_bf16 v[50:65], v[146:149], v[162:165], v[50:65]
	s_waitcnt lgkmcnt(1)
	v_mfma_f32_32x32x16_bf16 v[34:49], v[146:149], v[174:177], v[34:49]
	ds_read_b128 v[146:149], v130 offset:23104
	ds_read_b128 v[182:185], v130 offset:23136
	s_waitcnt lgkmcnt(1)
	v_mfma_f32_32x32x16_bf16 v[18:33], v[146:149], v[162:165], v[18:33]
	v_mfma_f32_32x32x16_bf16 v[2:17], v[146:149], v[174:177], v[2:17]
	v_mfma_f32_32x32x16_bf16 v[50:65], v[166:169], v[170:173], v[50:65]
	v_mfma_f32_32x32x16_bf16 v[34:49], v[166:169], v[178:181], v[34:49]
	s_waitcnt lgkmcnt(0)
	v_mfma_f32_32x32x16_bf16 v[18:33], v[182:185], v[170:173], v[18:33]
	v_mfma_f32_32x32x16_bf16 v[2:17], v[182:185], v[178:181], v[2:17]
	s_cbranch_vccnz .LBB0_358
	s_waitcnt vmcnt(8)
	ds_write_b128 v150, v[66:69]
	ds_write_b128 v150, v[70:73] offset:4608
	ds_write_b128 v150, v[74:77] offset:9216
	ds_write_b128 v150, v[78:81] offset:13824
	ds_write_b128 v150, v[82:85] offset:36864
	ds_write_b128 v150, v[86:89] offset:41472
	ds_write_b128 v150, v[98:101] offset:46080
	ds_write_b128 v150, v[110:113] offset:50688
	s_branch .LBB0_358

.LBB0_609:
	v_lshl_add_u64 v[150:151], v[150:151], 0, s[2:3]
	v_lshl_add_u64 v[152:153], v[152:153], 0, s[2:3]
	s_and_b64 vcc, exec, s[4:5]
	s_cbranch_vccnz .Lk10_exit
	s_add_i32 s20, s20, 2
	s_cmp_lt_u32 s20, 62
	s_cselect_b64 s[6:7], -1, 0
	s_cmp_gt_u32 s20, 61
	s_cselect_b64 s[4:5], -1, 0
	s_and_b64 vcc, exec, s[4:5]
	v_lshl_add_u64 v[156:157], v[152:153], 0, v[146:147]
	v_lshl_add_u64 v[154:155], v[150:151], 0, v[146:147]
	s_cbranch_vccnz .Lk10_noP0
	v_add_co_u32_e32 v64, vcc, 0xb6c0000, v156
	s_nop 1
	v_addc_co_u32_e32 v65, vcc, 0, v157, vcc
	v_add_co_u32_e32 v68, vcc, 0xb700000, v156
	s_nop 1
	v_addc_co_u32_e32 v69, vcc, 0, v157, vcc
	v_add_co_u32_e32 v72, vcc, 0xb740000, v156
	global_load_dwordx4 v[64:67], v[64:65], off offset:512
	s_nop 0
	global_load_dwordx4 v[68:71], v[68:69], off offset:512
	v_addc_co_u32_e32 v73, vcc, 0, v157, vcc
	v_add_co_u32_e32 v80, vcc, 0xb780000, v156
	s_nop 1
	v_addc_co_u32_e32 v81, vcc, 0, v157, vcc
	global_load_dwordx4 v[72:75], v[72:73], off offset:512
	s_nop 0
	global_load_dwordx4 v[88:91], v[80:81], off offset:512
	v_add_co_u32_e32 v80, vcc, 0x2640000, v154
	s_nop 1
	v_addc_co_u32_e32 v81, vcc, 0, v155, vcc
	v_add_co_u32_e32 v92, vcc, 0x2680000, v154
	s_nop 1
	v_addc_co_u32_e32 v93, vcc, 0, v155, vcc
	v_add_co_u32_e32 v108, vcc, 0x26c0000, v154
	global_load_dwordx4 v[80:83], v[80:81], off offset:256
	s_nop 0
	global_load_dwordx4 v[92:95], v[92:93], off offset:256
	v_addc_co_u32_e32 v109, vcc, 0, v155, vcc
	v_add_co_u32_e32 v116, vcc, 0x2700000, v154
	s_nop 1
	v_addc_co_u32_e32 v117, vcc, 0, v155, vcc
	global_load_dwordx4 v[108:111], v[108:109], off offset:256
	s_nop 0
	global_load_dwordx4 v[116:119], v[116:117], off offset:256

.Lk10_join:
	s_cbranch_scc1 .Lk10_noP1
	v_add_co_u32_e32 v76, vcc, 0xb6c0000, v156
	s_nop 1
	v_addc_co_u32_e32 v77, vcc, 0, v157, vcc
	v_add_co_u32_e32 v84, vcc, 0xb700000, v156
	s_nop 1
	v_addc_co_u32_e32 v85, vcc, 0, v157, vcc
	v_add_co_u32_e32 v96, vcc, 0xb740000, v156
	global_load_dwordx4 v[76:79], v[76:77], off offset:640
	s_nop 0
	global_load_dwordx4 v[84:87], v[84:85], off offset:640
	v_addc_co_u32_e32 v97, vcc, 0, v157, vcc
	v_add_co_u32_e32 v100, vcc, 0xb780000, v156
	s_nop 1
	v_addc_co_u32_e32 v101, vcc, 0, v157, vcc
	v_add_co_u32_e32 v104, vcc, 0x2640000, v154
	global_load_dwordx4 v[96:99], v[96:97], off offset:640
	s_nop 0
	global_load_dwordx4 v[100:103], v[100:101], off offset:640
	v_addc_co_u32_e32 v105, vcc, 0, v155, vcc
	v_add_co_u32_e32 v112, vcc, 0x2680000, v154
	s_nop 1
	v_addc_co_u32_e32 v113, vcc, 0, v155, vcc
	v_add_co_u32_e32 v120, vcc, 0x26c0000, v154
	global_load_dwordx4 v[104:107], v[104:105], off offset:384
	s_nop 0
	global_load_dwordx4 v[112:115], v[112:113], off offset:384
	v_addc_co_u32_e32 v121, vcc, 0, v155, vcc
	v_add_co_u32_e32 v124, vcc, 0x2700000, v154
	s_nop 1
	v_addc_co_u32_e32 v125, vcc, 0, v155, vcc
	global_load_dwordx4 v[120:123], v[120:121], off offset:384
	s_nop 0
	global_load_dwordx4 v[124:127], v[124:125], off offset:384
.Lk10_noP1:
	s_waitcnt lgkmcnt(0)
	s_barrier
	v_mfma_f32_32x32x16_bf16 v[16:31], v[162:165], v[166:169], v[16:31]
	v_mfma_f32_32x32x16_bf16 v[0:15], v[162:165], v[178:181], v[0:15]
	v_mfma_f32_32x32x16_bf16 v[48:63], v[170:173], v[174:177], v[48:63]
	v_mfma_f32_32x32x16_bf16 v[32:47], v[170:173], v[182:185], v[32:47]
	v_mfma_f32_32x32x16_bf16 v[16:31], v[186:189], v[174:177], v[16:31]
	v_mfma_f32_32x32x16_bf16 v[0:15], v[186:189], v[182:185], v[0:15]
.LBB0_614:
	ds_read_b128 v[154:157], v130 offset:18432
	ds_read_b128 v[162:165], v158 offset:55296
	ds_read_b128 v[166:169], v130 offset:18464
	ds_read_b128 v[170:173], v158 offset:55328
	ds_read_b128 v[174:177], v158 offset:59904
	ds_read_b128 v[178:181], v158 offset:59936
	s_andn2_b64 vcc, exec, s[6:7]
	s_waitcnt lgkmcnt(4)
	v_mfma_f32_32x32x16_bf16 v[48:63], v[154:157], v[162:165], v[48:63]
	s_waitcnt lgkmcnt(1)
	v_mfma_f32_32x32x16_bf16 v[32:47], v[154:157], v[174:177], v[32:47]
	ds_read_b128 v[154:157], v130 offset:23040
	ds_read_b128 v[182:185], v130 offset:23072
	s_waitcnt lgkmcnt(1)
	v_mfma_f32_32x32x16_bf16 v[16:31], v[154:157], v[162:165], v[16:31]
	v_mfma_f32_32x32x16_bf16 v[0:15], v[154:157], v[174:177], v[0:15]
	v_mfma_f32_32x32x16_bf16 v[48:63], v[166:169], v[170:173], v[48:63]
	v_mfma_f32_32x32x16_bf16 v[32:47], v[166:169], v[178:181], v[32:47]
	s_waitcnt lgkmcnt(0)
	v_mfma_f32_32x32x16_bf16 v[16:31], v[182:185], v[170:173], v[16:31]
	ds_read_b128 v[154:157], v130 offset:18496
	ds_read_b128 v[162:165], v158 offset:55360
	ds_read_b128 v[166:169], v130 offset:18528
	ds_read_b128 v[170:173], v158 offset:55392
	v_mfma_f32_32x32x16_bf16 v[0:15], v[182:185], v[178:181], v[0:15]
	ds_read_b128 v[174:177], v158 offset:59968
	ds_read_b128 v[178:181], v158 offset:60000
	s_waitcnt lgkmcnt(4)
	v_mfma_f32_32x32x16_bf16 v[48:63], v[154:157], v[162:165], v[48:63]
	s_waitcnt lgkmcnt(1)
	v_mfma_f32_32x32x16_bf16 v[32:47], v[154:157], v[174:177], v[32:47]
	ds_read_b128 v[154:157], v130 offset:23104
	ds_read_b128 v[182:185], v130 offset:23136
	s_waitcnt lgkmcnt(1)
	v_mfma_f32_32x32x16_bf16 v[16:31], v[154:157], v[162:165], v[16:31]
	v_mfma_f32_32x32x16_bf16 v[0:15], v[154:157], v[174:177], v[0:15]
	v_mfma_f32_32x32x16_bf16 v[48:63], v[166:169], v[170:173], v[48:63]
	v_mfma_f32_32x32x16_bf16 v[32:47], v[166:169], v[178:181], v[32:47]
	s_waitcnt lgkmcnt(0)
	v_mfma_f32_32x32x16_bf16 v[16:31], v[182:185], v[170:173], v[16:31]
	v_mfma_f32_32x32x16_bf16 v[0:15], v[182:185], v[178:181], v[0:15]
	s_cbranch_vccnz .LBB0_609
	s_waitcnt vmcnt(8)
	ds_write_b128 v143, v[64:67]
	ds_write_b128 v143, v[68:71] offset:4608
	ds_write_b128 v143, v[72:75] offset:9216
	ds_write_b128 v143, v[88:91] offset:13824
	ds_write_b128 v143, v[80:83] offset:36864
	ds_write_b128 v143, v[92:95] offset:41472
	ds_write_b128 v143, v[108:111] offset:46080
	ds_write_b128 v143, v[116:119] offset:50688
	s_branch .LBB0_609
